# P4 SSD-output units: touch the chunk-state blocks (one dword per 64-B sector) as soon as the unit is known so the serialized gather rounds hit in L2
# baseline (speedup 1.0000x reference)
; #define QUEUE_LOOP(qi, total, ...) for (;;) { __syncthreads(); if (threadIdx.x == 0) ctlw[16] = __hip_atomic_fetch_add(qbase + 64 * (qi), 1u, __ATOMIC_RELAXED, __HIP_MEMORY_SCOPE_AGENT); \
;         __syncthreads(); const int u = (int)ctlw[16]; if (u >= (total)) break; __VA_ARGS__ }
; template <bool SAMPLE> ...
;     ...
;             const float* sp0 = SL + ((size_t)(sidx - c) * 64 + j16) * 128 + 16 * wid + 4 * ig;
; #pragma unroll
;             for (int q0 = 0; q0 < SEQ / 128 - 1; q0 += 4) if (q0 < c) {
;                 f32x4 tq[4][4]; float fq4[4];
; #pragma unroll
;                 for (int qq = 0; qq < 4; ++qq) { const bool on = q0 + qq < c; const int qe = on ? q0 + qq : 0; fq4[qq] = on ? facf[qe] : 0.f;
; #pragma unroll
;                     for (int pb = 0; pb < 4; ++pb) tq[qq][pb] = *(const f32x4*)(sp0 + ((size_t)qe * 64 + 16 * pb) * 128); }
; __device__ __forceinline__ void phase4(const Params& p, LAS unsigned char* lds, volatile LAS unsigned* ctlw, int vcu, int G, int qset) {
;     ...
;     QUEUE_LOOP(5, NBATCH * 16 * 8, { const int v = NBATCH * 16 * 8 - 1 - u;
;         ssd_out_unit<false>(p.ws, p.out, p.in[I_ALOG], p.in[I_DSKIP], p.in[I_SSDNW], p.in[I_SSM], p.in[I_SCONV], p.in[I_CONVW], p.in[I_CONVB], lds, (v >> 3) & 3, v >> 5, v & 7); })
.LBB0_1081:
	s_or_b64 exec, exec, s[2:3]
	s_waitcnt lgkmcnt(0)
	s_barrier
	ds_read_b32 v2, v1
	s_mov_b64 s[2:3], -1
	s_waitcnt lgkmcnt(0)
	v_cmp_lt_i32_e32 vcc, s30, v2
	v_readfirstlane_b32 s73, v2
	s_cbranch_vccnz .LBB0_1076
	s_sub_i32 s74, 0x1ff, s73
	s_and_b32 s70, s74, 7
	s_lshl_b32 s20, s70, 2
	v_mov_b32_e32 v88, v0
	v_mov_b32_e32 v2, s20
	global_load_dword v4, v2, s[56:57]
	global_load_dword v53, v2, s[58:59]
	v_readfirstlane_b32 s21, v88
	s_lshr_b32 s72, s74, 5
	s_ashr_i32 s4, s21, 6
	v_and_b32_e32 v86, 63, v88
	s_and_b32 s71, s74, 31
	s_lshl_b32 s99, s71, 19
	s_add_u32 s100, s6, s99
	s_addc_u32 s101, s7, 0
	v_lshlrev_b32_e32 v160, 6, v88
	s_mov_b32 s99, 0
.Lp4pf_loop:
	s_cmp_ge_u32 s99, s72
	s_cbranch_scc1 .Lp4pf_done
	global_load_dword v161, v160, s[100:101]
	s_add_u32 s100, s100, 0x8000
	s_addc_u32 s101, s101, 0
	s_add_i32 s99, s99, 1
	s_branch .Lp4pf_loop
.Lp4pf_done:
	s_cmp_gt_u32 s21, 63
	v_cmp_gt_u32_e32 vcc, 16, v86
	s_barrier
	s_cbranch_scc0 .LBB0_1090
	s_cmp_eq_u32 s4, 1
	s_cselect_b64 s[2:3], -1, 0
	s_and_b64 s[22:23], s[2:3], vcc
	s_and_saveexec_b64 s[2:3], s[22:23]
	s_cbranch_execz .LBB0_1089
	v_add_u32_e32 v5, 1, v86
	v_cmp_gt_u32_e32 vcc, s72, v5
	s_lshl_b32 s21, s71, 4
	v_add_lshl_u32 v50, s21, v86, 2
	v_mov_b32_e32 v6, 0
	s_and_saveexec_b64 s[22:23], vcc
	s_cbranch_execz .Lfac_noload
	global_load_dword v6, v50, s[16:17]
